# swiglu GEMM K-loop: merge 8 phases of 16 MFMA into 4 steps of 32 MFMA (8 barriers/iter instead of 16), vmcnt(8) per step
# speedup vs baseline: 1.0157x; 1.0157x over previous
; __device__ __forceinline__ int otid() { int t = threadIdx.x; asm volatile("" : "+v"(t)); return t; }
; #define PG8_STAGE(bufoff, gbase, voff) do { _Pragma("unroll") for (int _i = 0; _i < 2; ++_i) \
;         __builtin_amdgcn_global_load_lds((const unsigned*)((const char*)(gbase) + (voff)[_i]), (LAS unsigned*)(lds + (bufoff) + ldsw + _i * 8192), 16, 0, 0); } while (0)
; #define PG8_WAIT_V(n) asm volatile("s_waitcnt vmcnt(" #n ")" ::: "memory")
; #define PG8_BAR __builtin_amdgcn_s_barrier()
;     __device__ __forceinline__ Pre prefetch(const Unit& u, int wr, int fr) const { return pre_rows(ss, u.pm * 256 + wr * 64 + (int)(threadIdx.x & 63)); }
;     __device__ __forceinline__ Pre prefetch(const Unit& u, int wr, int fr) const { return pre_rows(ss, u.pm * 256 + wr * 64 + (int)(threadIdx.x & 63)); }
; template <class Epi>
; __device__ __forceinline__ void gemm_phase(LAS unsigned char* lds, const Gemm g, const Sched& S, const Epi& E) {
;     const int tid = otid(), wid = __builtin_amdgcn_readfirstlane(tid >> 6), lane = tid & 63, wr = wid >> 2, wc = wid & 3, fr = lane & 15, fq = lane >> 4;
;     const int nt = g.K / BK;
;     unsigned voffA[2], voffB[2];
; #pragma unroll
;     for (int i = 0; i < 2; ++i) { int R, C; stage_rc(tid * 16 + i * 8192, R, C); const int Rb = Epi::PERM ? ((R & ~31) + perm32(R & 31)) : R;
;         voffA[i] = (unsigned)(R * g.lda + C) * 2u; voffB[i] = (unsigned)(Rb * g.ldb + C) * 2u; }
;     const size_t kstep = (size_t)(BK * 2);
;     const size_t hstepA = (size_t)HALF * g.lda * 2, hstepB = (size_t)HALF * g.ldb * 2;
;     const unsigned ldsw = (unsigned)wid * 1024u;
;     const int aoff = lds_byte(wr * 64 + fr, fq * 8), boff = lds_byte(wc * 32 + fr, fq * 8);
;     ...
;     PG8_STAGE(PG8_SB(0, 0), cB, voffB); PG8_STAGE(PG8_SA(0, 0), cA, voffA); PG8_STAGE(PG8_SB(0, 1), cB + hstepB, voffB); PG8_STAGE(PG8_SA(0, 1), cA + hstepA, voffA);
;     if (wr == 1) PG8_BAR;
;     PG8_WAIT_V(4); PG8_BAR;
;     PG8_STAGE(PG8_SB(1, 0), cB + kstep, voffB); PG8_STAGE(PG8_SA(1, 0), cA + kstep, voffA); PG8_STAGE(PG8_SB(1, 1), cB + hstepB + kstep, voffB);
;     PG8_WAIT_V(6); PG8_BAR;
;     for (;;) {
;         const Pre pre = E.prefetch(cur, wr, fr);
;         const bool has_next = S.next(ui + 1, nxt);
;         const char* nA = has_next ? (const char*)g.A + nxt.ao : cA; const char* nB = has_next ? (const char*)g.Bt + nxt.bo : cB;
.LBB0_812:
	s_add_i32 m0, s33, 0x18000
	v_lshl_add_u64 v[2:3], v[2:3], 0, s[60:61]
	s_waitcnt vmcnt(0)
	s_barrier
	global_load_lds_dwordx4 v[2:3], off
	v_lshl_add_u64 v[2:3], v[4:5], 0, s[60:61]
	s_add_i32 m0, s33, 0x1a000
	s_add_i32 s75, s33, 0x8000
	global_load_lds_dwordx4 v[2:3], off
	v_lshl_add_u64 v[2:3], v[6:7], 0, s[60:61]
	s_mov_b32 m0, s75
	s_add_i32 s76, s33, 0xa000
	global_load_lds_dwordx4 v[2:3], off
	v_lshl_add_u64 v[2:3], v[8:9], 0, s[60:61]
	s_mov_b32 m0, s76
	s_sext_i32_i16 s55, s0
	global_load_lds_dwordx4 v[2:3], off
	s_add_i32 m0, s33, 0x1c000
	v_lshl_add_u64 v[2:3], v[10:11], 0, s[60:61]
	global_load_lds_dwordx4 v[2:3], off
	v_lshl_add_u64 v[2:3], v[12:13], 0, s[60:61]
	s_add_i32 m0, s33, 0x1e000
	s_lshl_b32 s0, s24, 6
	global_load_lds_dwordx4 v[2:3], off
	v_and_b32_e32 v2, 63, v219
	v_or_b32_e32 v147, s0, v2
	v_cvt_f32_u32_e32 v2, s74
	v_lshrrev_b32_e32 v21, 1, v20
	v_and_b32_e32 v21, 24, v21
	v_and_b32_e32 v141, 15, v20
	v_rcp_iflag_f32_e32 v2, v2
	v_lshlrev_b32_e32 v22, 1, v21
	v_lshlrev_b32_e32 v20, 2, v20
	s_lshl_b32 s1, s1, 5
	v_mul_f32_e32 v2, 0x4f7ffffe, v2
	v_cvt_u32_f32_e32 v2, v2
	v_lshl_or_b32 v22, v141, 6, v22
	s_lshl_b32 s24, s24, 13
	v_and_b32_e32 v20, 32, v20
	s_and_b32 s1, s1, 0x60
	v_readlane_b32 s36, v253, 61
	v_bitop3_b32 v23, v22, s24, v20 bitop3:0xde
	s_lshl_b32 s24, s1, 7
	s_add_i32 s77, s73, -2
	v_readlane_b32 s37, v253, 62
	s_cmp_eq_u64 s[36:37], 0
	s_cselect_b64 s[34:35], -1, 0
	s_cmp_lg_u64 s[36:37], 0
	v_or_b32_e32 v149, s1, v21
	v_readfirstlane_b32 s1, v2
	v_add_u32_e32 v2, v16, v14
	v_or_b32_e32 v143, s0, v141
	s_cselect_b64 s[36:37], -1, 0
	s_sub_i32 s0, 0, s74
	v_add_lshl_u32 v2, v2, v15, 1
	v_mov_b32_e32 v3, v1
	s_waitcnt vmcnt(6)
	s_mul_i32 s0, s0, s1
	v_lshl_add_u64 v[136:137], s[6:7], 0, v[2:3]
	v_add_u32_e32 v2, v19, v17
	s_mul_hi_u32 s0, s1, s0
	v_add_lshl_u32 v2, v2, v18, 1
	v_bitop3_b32 v145, v22, s24, v20 bitop3:0xde
	s_mov_b32 s27, s9
	s_mov_b32 s24, 0
	s_add_i32 s78, s1, s0
	v_lshl_add_u64 v[138:139], s[6:7], 0, v[2:3]
	v_add_u32_e32 v151, 0, v23
	s_barrier

; #define PG8_STAGE(bufoff, gbase, voff) do { _Pragma("unroll") for (int _i = 0; _i < 2; ++_i) \
;         __builtin_amdgcn_global_load_lds((const unsigned*)((const char*)(gbase) + (voff)[_i]), (LAS unsigned*)(lds + (bufoff) + ldsw + _i * 8192), 16, 0, 0); } while (0)
; #define PG8_LDA(dst, b, h) do { _Pragma("unroll") for (int m = 0; m < 4; ++m) _Pragma("unroll") for (int k = 0; k < 2; ++k) dst[m][k] = *(const LAS bf16x8*)(lds + PG8_SA(b, h) + aoff + m * 2048 + k * 1024); } while (0)
; #define PG8_LDB(dst, b, h) do { _Pragma("unroll") for (int n = 0; n < 2; ++n) _Pragma("unroll") for (int k = 0; k < 2; ++k) dst[n][k] = *(const LAS bf16x8*)(lds + PG8_SB(b, h) + boff + n * 2048 + k * 1024); } while (0)
; #define PG8_MMA(ai, bj, At, Bt) do { __builtin_amdgcn_s_setprio(1); _Pragma("unroll") for (int m = 0; m < 4; ++m) _Pragma("unroll") for (int n = 0; n < 2; ++n) _Pragma("unroll") for (int k = 0; k < 2; ++k) \
;         acc[ai][bj][m][n] = __builtin_amdgcn_mfma_f32_16x16x32_bf16(Bt[n][k], At[m][k], acc[ai][bj][m][n], 0, 0, 0); __builtin_amdgcn_s_setprio(0); } while (0)
; #define PG8_WAIT_L(n) asm volatile("s_waitcnt lgkmcnt(" #n ")" ::: "memory")
; #define PG8_BAR __builtin_amdgcn_s_barrier()
; #define PG8_SCHED __builtin_amdgcn_sched_barrier(0)
; template <class Epi>
; __device__ __forceinline__ void gemm_phase(LAS unsigned char* lds, const Gemm g, const Sched& S, const Epi& E) {
;     ...
;         for (int t = 0; t < nt; t += 2) {
;             const bool last = (t == nt - 2);
;             const char* a1 = cA + (size_t)(t + 1) * kstep;
;             const char* a2 = last ? nA : cA + (size_t)(t + 2) * kstep; const char* b2 = last ? nB : cB + (size_t)(t + 2) * kstep;
;             const char* a3 = a2 + kstep; const char* b3 = b2 + kstep;
;             PG8_LDB(B0, 0, 0); PG8_SCHED; PG8_LDA(At, 0, 0); PG8_STAGE(PG8_SA(1, 1), a1 + hstepA, voffA);
;             PG8_WAIT_L(8); PG8_BAR; PG8_WAIT_L(0); PG8_MMA(0, 0, At, B0); PG8_BAR; PG8_SCHED;
;             PG8_LDB(B1, 0, 1); PG8_STAGE(PG8_SB(0, 0), b2, voffB);
;             PG8_BAR; PG8_WAIT_L(0); PG8_MMA(0, 1, At, B1); PG8_BAR;
;             PG8_LDA(At, 0, 1); PG8_STAGE(PG8_SA(0, 0), a2, voffA);
.LBB0_825:
	s_add_i32 s86, s68, 2
	s_add_u32 s70, s4, 0x80
	s_addc_u32 s69, s5, 0
	s_add_i32 s87, 0, 0x10000
	v_add_u32_e32 v144, s87, v145
	ds_read_b128 v[152:155], v144
	ds_read_b128 v[156:159], v144 offset:1024
	ds_read_b128 v[160:163], v144 offset:2048
	ds_read_b128 v[164:167], v144 offset:3072
	s_cmp_eq_u32 s77, s68
	s_cselect_b32 s68, s59, s70
	s_cselect_b32 s69, s57, s69
	s_cselect_b32 s71, s82, s85
	s_cselect_b32 s70, s83, s84
	v_lshl_add_u64 v[192:193], s[4:5], 0, v[136:137]
	s_add_i32 m0, s33, 0xc000
	ds_read_b128 v[168:171], v151
	ds_read_b128 v[172:175], v151 offset:1024
	ds_read_b128 v[176:179], v151 offset:2048
	ds_read_b128 v[180:183], v151 offset:3072
	ds_read_b128 v[184:187], v151 offset:4096
	ds_read_b128 v[188:191], v151 offset:5120
	ds_read_b128 v[196:199], v151 offset:6144
	ds_read_b128 v[200:203], v151 offset:7168
	global_load_lds_dwordx4 v[192:193], off
	v_lshl_add_u64 v[192:193], s[4:5], 0, v[138:139]
	s_add_i32 m0, s33, 0xe000
	s_nop 0
	global_load_lds_dwordx4 v[192:193], off
	s_add_i32 s88, 0, 0x14000
	v_add_u32_e32 v144, s88, v145
	ds_read_b128 v[204:207], v144
	ds_read_b128 v[208:211], v144 offset:1024
	ds_read_b128 v[212:215], v144 offset:2048
	ds_read_b128 v[234:237], v144 offset:3072
	s_waitcnt vmcnt(8)
	s_waitcnt lgkmcnt(0)
	s_barrier
	s_setprio 1
	v_mfma_f32_16x16x32_bf16 v[126:129], v[152:155], v[168:171], v[126:129]
	v_mfma_f32_16x16x32_bf16 v[122:125], v[160:163], v[168:171], v[122:125]
	v_mfma_f32_16x16x32_bf16 v[110:113], v[152:155], v[176:179], v[110:113]
	v_mfma_f32_16x16x32_bf16 v[106:109], v[160:163], v[176:179], v[106:109]
	v_mfma_f32_16x16x32_bf16 v[94:97], v[152:155], v[184:187], v[94:97]
	v_mfma_f32_16x16x32_bf16 v[90:93], v[160:163], v[184:187], v[90:93]
	v_mfma_f32_16x16x32_bf16 v[78:81], v[152:155], v[196:199], v[78:81]
	v_mfma_f32_16x16x32_bf16 v[74:77], v[160:163], v[196:199], v[74:77]
	v_mfma_f32_16x16x32_bf16 v[126:129], v[156:159], v[172:175], v[126:129]
	v_mfma_f32_16x16x32_bf16 v[122:125], v[164:167], v[172:175], v[122:125]
	v_mfma_f32_16x16x32_bf16 v[110:113], v[156:159], v[180:183], v[110:113]
	v_mfma_f32_16x16x32_bf16 v[106:109], v[164:167], v[180:183], v[106:109]
	v_mfma_f32_16x16x32_bf16 v[94:97], v[156:159], v[188:191], v[94:97]
	v_mfma_f32_16x16x32_bf16 v[90:93], v[164:167], v[188:191], v[90:93]
	v_mfma_f32_16x16x32_bf16 v[78:81], v[156:159], v[200:203], v[78:81]
	v_mfma_f32_16x16x32_bf16 v[74:77], v[164:167], v[200:203], v[74:77]
	v_mfma_f32_16x16x32_bf16 v[118:121], v[204:207], v[168:171], v[118:121]
	v_mfma_f32_16x16x32_bf16 v[114:117], v[212:215], v[168:171], v[114:117]
	v_mfma_f32_16x16x32_bf16 v[102:105], v[204:207], v[176:179], v[102:105]
	v_mfma_f32_16x16x32_bf16 v[98:101], v[212:215], v[176:179], v[98:101]
	v_mfma_f32_16x16x32_bf16 v[86:89], v[204:207], v[184:187], v[86:89]
	v_mfma_f32_16x16x32_bf16 v[82:85], v[212:215], v[184:187], v[82:85]
	v_mfma_f32_16x16x32_bf16 v[70:73], v[204:207], v[196:199], v[70:73]
	v_mfma_f32_16x16x32_bf16 v[66:69], v[212:215], v[196:199], v[66:69]
	v_mfma_f32_16x16x32_bf16 v[118:121], v[208:211], v[172:175], v[118:121]
	v_mfma_f32_16x16x32_bf16 v[114:117], v[234:237], v[172:175], v[114:117]
	v_mfma_f32_16x16x32_bf16 v[102:105], v[208:211], v[180:183], v[102:105]
	v_mfma_f32_16x16x32_bf16 v[98:101], v[234:237], v[180:183], v[98:101]
	v_mfma_f32_16x16x32_bf16 v[86:89], v[208:211], v[188:191], v[86:89]
	v_mfma_f32_16x16x32_bf16 v[82:85], v[234:237], v[188:191], v[82:85]
	v_mfma_f32_16x16x32_bf16 v[70:73], v[208:211], v[200:203], v[70:73]
	v_mfma_f32_16x16x32_bf16 v[66:69], v[234:237], v[200:203], v[66:69]
	s_setprio 0
	s_barrier
	s_add_i32 s87, s87, s51
	v_lshl_add_u64 v[192:193], s[70:71], 0, v[0:1]
	s_mov_b32 m0, s87
	s_nop 0
	global_load_lds_dwordx4 v[192:193], off
	v_lshl_add_u64 v[216:217], s[70:71], 0, v[134:135]
	s_add_i32 m0, s87, 0x2000
	s_nop 0
	global_load_lds_dwordx4 v[216:217], off
	s_mov_b32 m0, s33
	v_lshl_add_u64 v[222:223], s[68:69], 0, v[130:131]
	ds_read_b128 v[168:171], v151 offset:16384
	ds_read_b128 v[172:175], v151 offset:17408
	ds_read_b128 v[176:179], v151 offset:18432
	ds_read_b128 v[180:183], v151 offset:19456
	ds_read_b128 v[184:187], v151 offset:20480
	ds_read_b128 v[188:191], v151 offset:21504
	ds_read_b128 v[196:199], v151 offset:22528
	ds_read_b128 v[200:203], v151 offset:23552
	global_load_lds_dwordx4 v[222:223], off
	v_lshl_add_u64 v[224:225], s[68:69], 0, v[132:133]
	s_mov_b32 m0, s48
	s_nop 0
	global_load_lds_dwordx4 v[224:225], off
	s_add_u32 s70, s70, s14
	s_addc_u32 s71, s71, s15
	s_add_i32 s87, s88, s51
	v_lshl_add_u64 v[226:227], s[70:71], 0, v[0:1]
	s_mov_b32 m0, s87
	v_lshl_add_u64 v[228:229], s[70:71], 0, v[134:135]
	global_load_lds_dwordx4 v[226:227], off
	s_add_i32 m0, s87, 0x2000
	s_nop 0
	global_load_lds_dwordx4 v[228:229], off
	s_waitcnt vmcnt(8)
	s_waitcnt lgkmcnt(0)
	s_barrier
; #define PG8_STAGE(bufoff, gbase, voff) do { _Pragma("unroll") for (int _i = 0; _i < 2; ++_i) \
;         __builtin_amdgcn_global_load_lds((const unsigned*)((const char*)(gbase) + (voff)[_i]), (LAS unsigned*)(lds + (bufoff) + ldsw + _i * 8192), 16, 0, 0); } while (0)
; #define PG8_LDA(dst, b, h) do { _Pragma("unroll") for (int m = 0; m < 4; ++m) _Pragma("unroll") for (int k = 0; k < 2; ++k) dst[m][k] = *(const LAS bf16x8*)(lds + PG8_SA(b, h) + aoff + m * 2048 + k * 1024); } while (0)
; #define PG8_LDB(dst, b, h) do { _Pragma("unroll") for (int n = 0; n < 2; ++n) _Pragma("unroll") for (int k = 0; k < 2; ++k) dst[n][k] = *(const LAS bf16x8*)(lds + PG8_SB(b, h) + boff + n * 2048 + k * 1024); } while (0)
; #define PG8_MMA(ai, bj, At, Bt) do { __builtin_amdgcn_s_setprio(1); _Pragma("unroll") for (int m = 0; m < 4; ++m) _Pragma("unroll") for (int n = 0; n < 2; ++n) _Pragma("unroll") for (int k = 0; k < 2; ++k) \
;         acc[ai][bj][m][n] = __builtin_amdgcn_mfma_f32_16x16x32_bf16(Bt[n][k], At[m][k], acc[ai][bj][m][n], 0, 0, 0); __builtin_amdgcn_s_setprio(0); } while (0)
; #define PG8_WAIT_V(n) asm volatile("s_waitcnt vmcnt(" #n ")" ::: "memory")
; #define PG8_WAIT_L(n) asm volatile("s_waitcnt lgkmcnt(" #n ")" ::: "memory")
; #define PG8_BAR __builtin_amdgcn_s_barrier()
; #define PG8_SCHED __builtin_amdgcn_sched_barrier(0)
; template <class Epi>
; __device__ __forceinline__ void gemm_phase(LAS unsigned char* lds, const Gemm g, const Sched& S, const Epi& E) {
;     ...
;             PG8_BAR; PG8_WAIT_L(0); PG8_MMA(0, 1, At, B1); PG8_BAR;
;             PG8_LDA(At, 0, 1); PG8_STAGE(PG8_SA(0, 0), a2, voffA);
;             PG8_BAR; PG8_WAIT_L(0); PG8_MMA(1, 0, At, B0); PG8_BAR; PG8_SCHED;
;             PG8_STAGE(PG8_SB(0, 1), b2 + hstepB, voffB);
;             PG8_WAIT_V(6); PG8_BAR; PG8_MMA(1, 1, At, B1); PG8_BAR;
;             PG8_LDB(B0, 1, 0); PG8_SCHED; PG8_LDA(At, 1, 0); PG8_STAGE(PG8_SA(0, 1), a2 + hstepA, voffA);
;             PG8_WAIT_L(8); PG8_BAR; PG8_WAIT_L(0); PG8_MMA(0, 0, At, B0); PG8_BAR; PG8_SCHED;
	s_setprio 1
	v_mfma_f32_16x16x32_bf16 v[62:65], v[152:155], v[168:171], v[62:65]
	v_mfma_f32_16x16x32_bf16 v[58:61], v[160:163], v[168:171], v[58:61]
	v_mfma_f32_16x16x32_bf16 v[46:49], v[152:155], v[176:179], v[46:49]
	v_mfma_f32_16x16x32_bf16 v[42:45], v[160:163], v[176:179], v[42:45]
	v_mfma_f32_16x16x32_bf16 v[30:33], v[152:155], v[184:187], v[30:33]
	v_mfma_f32_16x16x32_bf16 v[26:29], v[160:163], v[184:187], v[26:29]
	v_mfma_f32_16x16x32_bf16 v[14:17], v[152:155], v[196:199], v[14:17]
	v_mfma_f32_16x16x32_bf16 v[10:13], v[160:163], v[196:199], v[10:13]
	v_mfma_f32_16x16x32_bf16 v[62:65], v[156:159], v[172:175], v[62:65]
	v_mfma_f32_16x16x32_bf16 v[58:61], v[164:167], v[172:175], v[58:61]
	v_mfma_f32_16x16x32_bf16 v[46:49], v[156:159], v[180:183], v[46:49]
	v_mfma_f32_16x16x32_bf16 v[42:45], v[164:167], v[180:183], v[42:45]
	v_mfma_f32_16x16x32_bf16 v[30:33], v[156:159], v[188:191], v[30:33]
	v_mfma_f32_16x16x32_bf16 v[26:29], v[164:167], v[188:191], v[26:29]
	v_mfma_f32_16x16x32_bf16 v[14:17], v[156:159], v[200:203], v[14:17]
	v_mfma_f32_16x16x32_bf16 v[10:13], v[164:167], v[200:203], v[10:13]
	v_mfma_f32_16x16x32_bf16 v[54:57], v[204:207], v[168:171], v[54:57]
	v_mfma_f32_16x16x32_bf16 v[50:53], v[212:215], v[168:171], v[50:53]
	v_mfma_f32_16x16x32_bf16 v[38:41], v[204:207], v[176:179], v[38:41]
	v_mfma_f32_16x16x32_bf16 v[34:37], v[212:215], v[176:179], v[34:37]
	v_mfma_f32_16x16x32_bf16 v[22:25], v[204:207], v[184:187], v[22:25]
	v_mfma_f32_16x16x32_bf16 v[18:21], v[212:215], v[184:187], v[18:21]
	v_mfma_f32_16x16x32_bf16 v[6:9], v[204:207], v[196:199], v[6:9]
	v_mfma_f32_16x16x32_bf16 v[2:5], v[212:215], v[196:199], v[2:5]
	v_mfma_f32_16x16x32_bf16 v[54:57], v[208:211], v[172:175], v[54:57]
	v_mfma_f32_16x16x32_bf16 v[50:53], v[234:237], v[172:175], v[50:53]
	v_mfma_f32_16x16x32_bf16 v[38:41], v[208:211], v[180:183], v[38:41]
	v_mfma_f32_16x16x32_bf16 v[34:37], v[234:237], v[180:183], v[34:37]
	v_mfma_f32_16x16x32_bf16 v[22:25], v[208:211], v[188:191], v[22:25]
	v_mfma_f32_16x16x32_bf16 v[18:21], v[234:237], v[188:191], v[18:21]
	v_mfma_f32_16x16x32_bf16 v[6:9], v[208:211], v[200:203], v[6:9]
	v_mfma_f32_16x16x32_bf16 v[2:5], v[234:237], v[200:203], v[2:5]
	s_setprio 0
	s_barrier
	s_add_i32 s70, 0, 0x18000
	v_add_u32_e32 v144, s70, v145
	ds_read_b128 v[152:155], v144
	ds_read_b128 v[156:159], v144 offset:1024
	ds_read_b128 v[160:163], v144 offset:2048
	ds_read_b128 v[164:167], v144 offset:3072
	s_add_u32 s68, s68, s6
	s_addc_u32 s69, s69, s7
	s_mov_b32 m0, s58
	v_lshl_add_u64 v[204:205], s[68:69], 0, v[130:131]
	ds_read_b128 v[168:171], v151 offset:32768
	ds_read_b128 v[172:175], v151 offset:33792
	ds_read_b128 v[176:179], v151 offset:34816
	ds_read_b128 v[180:183], v151 offset:35840
	ds_read_b128 v[184:187], v151 offset:36864
	ds_read_b128 v[188:191], v151 offset:37888
	ds_read_b128 v[196:199], v151 offset:38912
	ds_read_b128 v[200:203], v151 offset:39936
	global_load_lds_dwordx4 v[204:205], off
	v_lshl_add_u64 v[204:205], s[68:69], 0, v[132:133]
	s_mov_b32 m0, s72
	s_nop 0
	global_load_lds_dwordx4 v[204:205], off
	s_add_i32 s68, 0, 0x1c000
	v_add_u32_e32 v144, s68, v145
	ds_read_b128 v[204:207], v144
	ds_read_b128 v[208:211], v144 offset:1024
	ds_read_b128 v[212:215], v144 offset:2048
	ds_read_b128 v[234:237], v144 offset:3072
	s_waitcnt vmcnt(8)
	s_waitcnt lgkmcnt(0)
	s_barrier
	s_setprio 1
	v_mfma_f32_16x16x32_bf16 v[126:129], v[152:155], v[168:171], v[126:129]
	v_mfma_f32_16x16x32_bf16 v[122:125], v[160:163], v[168:171], v[122:125]
	v_mfma_f32_16x16x32_bf16 v[110:113], v[152:155], v[176:179], v[110:113]
	v_mfma_f32_16x16x32_bf16 v[106:109], v[160:163], v[176:179], v[106:109]
	v_mfma_f32_16x16x32_bf16 v[94:97], v[152:155], v[184:187], v[94:97]
	v_mfma_f32_16x16x32_bf16 v[90:93], v[160:163], v[184:187], v[90:93]
	v_mfma_f32_16x16x32_bf16 v[78:81], v[152:155], v[196:199], v[78:81]
	v_mfma_f32_16x16x32_bf16 v[74:77], v[160:163], v[196:199], v[74:77]
	v_mfma_f32_16x16x32_bf16 v[126:129], v[156:159], v[172:175], v[126:129]
	v_mfma_f32_16x16x32_bf16 v[122:125], v[164:167], v[172:175], v[122:125]
	v_mfma_f32_16x16x32_bf16 v[110:113], v[156:159], v[180:183], v[110:113]
	v_mfma_f32_16x16x32_bf16 v[106:109], v[164:167], v[180:183], v[106:109]
	v_mfma_f32_16x16x32_bf16 v[94:97], v[156:159], v[188:191], v[94:97]
	v_mfma_f32_16x16x32_bf16 v[90:93], v[164:167], v[188:191], v[90:93]
	v_mfma_f32_16x16x32_bf16 v[78:81], v[156:159], v[200:203], v[78:81]
	v_mfma_f32_16x16x32_bf16 v[74:77], v[164:167], v[200:203], v[74:77]
	v_mfma_f32_16x16x32_bf16 v[118:121], v[204:207], v[168:171], v[118:121]
	v_mfma_f32_16x16x32_bf16 v[114:117], v[212:215], v[168:171], v[114:117]
	v_mfma_f32_16x16x32_bf16 v[102:105], v[204:207], v[176:179], v[102:105]
	v_mfma_f32_16x16x32_bf16 v[98:101], v[212:215], v[176:179], v[98:101]
	v_mfma_f32_16x16x32_bf16 v[86:89], v[204:207], v[184:187], v[86:89]
	v_mfma_f32_16x16x32_bf16 v[82:85], v[212:215], v[184:187], v[82:85]
	v_mfma_f32_16x16x32_bf16 v[70:73], v[204:207], v[196:199], v[70:73]
	v_mfma_f32_16x16x32_bf16 v[66:69], v[212:215], v[196:199], v[66:69]
	v_mfma_f32_16x16x32_bf16 v[118:121], v[208:211], v[172:175], v[118:121]
	v_mfma_f32_16x16x32_bf16 v[114:117], v[234:237], v[172:175], v[114:117]
	v_mfma_f32_16x16x32_bf16 v[102:105], v[208:211], v[180:183], v[102:105]
	v_mfma_f32_16x16x32_bf16 v[98:101], v[234:237], v[180:183], v[98:101]
	v_mfma_f32_16x16x32_bf16 v[86:89], v[208:211], v[188:191], v[86:89]
	v_mfma_f32_16x16x32_bf16 v[82:85], v[234:237], v[188:191], v[82:85]
	v_mfma_f32_16x16x32_bf16 v[70:73], v[208:211], v[200:203], v[70:73]
	v_mfma_f32_16x16x32_bf16 v[66:69], v[234:237], v[200:203], v[66:69]
	s_setprio 0
	s_barrier
; __device__ __forceinline__ float pre_get(const Pre& p, int ai, int m, int fr) { return __shfl(p.v[ai], m * 16 + fr); }
; __device__ __forceinline__ float rstd_pre(const float* ss, float v) { return ss ? rsqrtf(v * (1.0f / 2048.0f) + 1e-6f) : 1.0f; }
; #define PG8_STAGE(bufoff, gbase, voff) do { _Pragma("unroll") for (int _i = 0; _i < 2; ++_i) \
;         __builtin_amdgcn_global_load_lds((const unsigned*)((const char*)(gbase) + (voff)[_i]), (LAS unsigned*)(lds + (bufoff) + ldsw + _i * 8192), 16, 0, 0); } while (0)
; #define PG8_LDA(dst, b, h) do { _Pragma("unroll") for (int m = 0; m < 4; ++m) _Pragma("unroll") for (int k = 0; k < 2; ++k) dst[m][k] = *(const LAS bf16x8*)(lds + PG8_SA(b, h) + aoff + m * 2048 + k * 1024); } while (0)
; #define PG8_LDB(dst, b, h) do { _Pragma("unroll") for (int n = 0; n < 2; ++n) _Pragma("unroll") for (int k = 0; k < 2; ++k) dst[n][k] = *(const LAS bf16x8*)(lds + PG8_SB(b, h) + boff + n * 2048 + k * 1024); } while (0)
; #define PG8_WAIT_V(n) asm volatile("s_waitcnt vmcnt(" #n ")" ::: "memory")
; #define PG8_WAIT_L(n) asm volatile("s_waitcnt lgkmcnt(" #n ")" ::: "memory")
; #define PG8_BAR __builtin_amdgcn_s_barrier()
; template <class Epi>
; __device__ __forceinline__ void gemm_phase(LAS unsigned char* lds, const Gemm g, const Sched& S, const Epi& E) {
;     ...
;             PG8_LDB(B0, 1, 0); PG8_SCHED; PG8_LDA(At, 1, 0); PG8_STAGE(PG8_SA(0, 1), a2 + hstepA, voffA);
;             PG8_WAIT_L(8); PG8_BAR; PG8_WAIT_L(0); PG8_MMA(0, 0, At, B0); PG8_BAR; PG8_SCHED;
;             PG8_LDB(B1, 1, 1); PG8_STAGE(PG8_SB(1, 0), b3, voffB);
;             PG8_BAR; PG8_WAIT_L(0); PG8_MMA(0, 1, At, B1); PG8_BAR;
;             PG8_LDA(At, 1, 1); PG8_STAGE(PG8_SA(1, 0), a3, voffA);
;             PG8_BAR; PG8_WAIT_L(0); PG8_MMA(1, 0, At, B0); PG8_BAR; PG8_SCHED;
;             PG8_STAGE(PG8_SB(1, 1), b3 + hstepB, voffB);
;             PG8_WAIT_V(6); PG8_BAR; PG8_MMA(1, 1, At, B1); PG8_BAR;
;         }
;     __device__ __forceinline__ void operator()(const Acc& acc, const Unit& u, int wr, int wc, int fr, int fq, const Pre& pre) const {
;         const int row0 = u.pm * 256 + wr * 64 + fr, col0 = u.pn * 128 + wc * 32 + 8 * fq;
;         float rsq[2][4];
; #pragma unroll
;         for (int ai = 0; ai < 2; ++ai)
; #pragma unroll
;             for (int m = 0; m < 4; ++m) rsq[ai][m] = rstd_pre(ss, pre_get(pre, ai, m, fr));
	s_add_i32 s69, s70, s51
	v_lshl_add_u64 v[192:193], v[192:193], 0, s[60:61]
	s_mov_b32 m0, s69
	s_nop 0
	global_load_lds_dwordx4 v[192:193], off
	v_lshl_add_u64 v[192:193], v[216:217], 0, s[60:61]
	s_add_i32 m0, s69, 0x2000
	s_nop 0
	global_load_lds_dwordx4 v[192:193], off
	s_mov_b32 m0, s75
	v_lshl_add_u64 v[192:193], v[222:223], 0, s[60:61]
	ds_read_b128 v[168:171], v151 offset:49152
	ds_read_b128 v[172:175], v151 offset:50176
	ds_read_b128 v[176:179], v151 offset:51200
	ds_read_b128 v[180:183], v151 offset:52224
	ds_read_b128 v[184:187], v151 offset:53248
	ds_read_b128 v[188:191], v151 offset:54272
	ds_read_b128 v[196:199], v151 offset:55296
	ds_read_b128 v[200:203], v151 offset:56320
	global_load_lds_dwordx4 v[192:193], off
	v_lshl_add_u64 v[192:193], v[224:225], 0, s[60:61]
	s_mov_b32 m0, s76
	s_nop 0
	global_load_lds_dwordx4 v[192:193], off
	s_add_i32 s68, s68, s51
	v_lshl_add_u64 v[192:193], v[226:227], 0, s[60:61]
	s_mov_b32 m0, s68
	s_nop 0
	global_load_lds_dwordx4 v[192:193], off
	v_lshl_add_u64 v[192:193], v[228:229], 0, s[60:61]
	s_add_i32 m0, s68, 0x2000
	s_nop 0
	global_load_lds_dwordx4 v[192:193], off
	s_waitcnt vmcnt(8)
	s_waitcnt lgkmcnt(0)
	s_barrier
	s_setprio 1
	v_mfma_f32_16x16x32_bf16 v[62:65], v[152:155], v[168:171], v[62:65]
	v_mfma_f32_16x16x32_bf16 v[58:61], v[160:163], v[168:171], v[58:61]
	v_mfma_f32_16x16x32_bf16 v[46:49], v[152:155], v[176:179], v[46:49]
	v_mfma_f32_16x16x32_bf16 v[42:45], v[160:163], v[176:179], v[42:45]
	v_mfma_f32_16x16x32_bf16 v[30:33], v[152:155], v[184:187], v[30:33]
	v_mfma_f32_16x16x32_bf16 v[26:29], v[160:163], v[184:187], v[26:29]
	v_mfma_f32_16x16x32_bf16 v[14:17], v[152:155], v[196:199], v[14:17]
	v_mfma_f32_16x16x32_bf16 v[10:13], v[160:163], v[196:199], v[10:13]
	v_mfma_f32_16x16x32_bf16 v[62:65], v[156:159], v[172:175], v[62:65]
	v_mfma_f32_16x16x32_bf16 v[58:61], v[164:167], v[172:175], v[58:61]
	v_mfma_f32_16x16x32_bf16 v[46:49], v[156:159], v[180:183], v[46:49]
	v_mfma_f32_16x16x32_bf16 v[42:45], v[164:167], v[180:183], v[42:45]
	v_mfma_f32_16x16x32_bf16 v[30:33], v[156:159], v[188:191], v[30:33]
	v_mfma_f32_16x16x32_bf16 v[26:29], v[164:167], v[188:191], v[26:29]
	v_mfma_f32_16x16x32_bf16 v[14:17], v[156:159], v[200:203], v[14:17]
	v_mfma_f32_16x16x32_bf16 v[10:13], v[164:167], v[200:203], v[10:13]
	v_mfma_f32_16x16x32_bf16 v[54:57], v[204:207], v[168:171], v[54:57]
	v_mfma_f32_16x16x32_bf16 v[50:53], v[212:215], v[168:171], v[50:53]
	v_mfma_f32_16x16x32_bf16 v[38:41], v[204:207], v[176:179], v[38:41]
	v_mfma_f32_16x16x32_bf16 v[34:37], v[212:215], v[176:179], v[34:37]
	v_mfma_f32_16x16x32_bf16 v[22:25], v[204:207], v[184:187], v[22:25]
	v_mfma_f32_16x16x32_bf16 v[18:21], v[212:215], v[184:187], v[18:21]
	v_mfma_f32_16x16x32_bf16 v[6:9], v[204:207], v[196:199], v[6:9]
	v_mfma_f32_16x16x32_bf16 v[2:5], v[212:215], v[196:199], v[2:5]
	v_mfma_f32_16x16x32_bf16 v[54:57], v[208:211], v[172:175], v[54:57]
	v_mfma_f32_16x16x32_bf16 v[50:53], v[234:237], v[172:175], v[50:53]
	v_mfma_f32_16x16x32_bf16 v[38:41], v[208:211], v[180:183], v[38:41]
	v_mfma_f32_16x16x32_bf16 v[34:37], v[234:237], v[180:183], v[34:37]
	v_mfma_f32_16x16x32_bf16 v[22:25], v[208:211], v[188:191], v[22:25]
	v_mfma_f32_16x16x32_bf16 v[18:21], v[234:237], v[188:191], v[18:21]
	v_mfma_f32_16x16x32_bf16 v[6:9], v[208:211], v[200:203], v[6:9]
	v_mfma_f32_16x16x32_bf16 v[2:5], v[234:237], v[200:203], v[2:5]
	s_setprio 0
	s_add_u32 s4, s4, 0x100
	s_addc_u32 s5, s5, 0
	s_add_u32 s84, s84, 0x100
	s_addc_u32 s85, s85, 0
	s_cmp_ge_u32 s86, s73
	s_mov_b32 s68, s86
	s_barrier
	s_cbranch_scc0 .LBB0_825
	v_and_or_b32 v144, v220, 64, v141
	v_lshlrev_b32_e32 v160, 2, v144
	ds_bpermute_b32 v155, v160, v142
	ds_bpermute_b32 v154, v160, v142 offset:64
	s_mov_b32 s4, 0x358637bd
	v_mov_b64_e32 v[156:157], s[4:5]
	s_mov_b32 s8, 0x3a000000
	v_lshl_add_u32 v153, s81, 8, v143
	s_waitcnt lgkmcnt(0)
	v_pk_fma_f32 v[158:159], v[154:155], s[8:9], v[156:157] op_sel_hi:[1,0,0]
	s_mov_b32 s81, s80
	v_mul_f32_e32 v144, 0x4b800000, v159
	v_cmp_gt_f32_e64 s[4:5], s97, v159
	v_cmp_gt_f32_e32 vcc, s97, v158
	s_mov_b64 s[68:69], s[66:67]
	v_cndmask_b32_e64 v144, v159, v144, s[4:5]
	v_rsq_f32_e32 v144, v144
	ds_bpermute_b32 v159, v160, v142 offset:128
	v_mul_f32_e32 v146, 0x45800000, v144
	v_cndmask_b32_e64 v144, v144, v146, s[4:5]
	v_cndmask_b32_e64 v154, v144, 1.0, s[34:35]
	v_mul_f32_e32 v144, 0x4b800000, v158
	v_cndmask_b32_e32 v144, v158, v144, vcc
	ds_bpermute_b32 v158, v160, v142 offset:192
	v_rsq_f32_e32 v144, v144
	s_waitcnt lgkmcnt(0)
	v_pk_fma_f32 v[158:159], v[158:159], s[8:9], v[156:157] op_sel_hi:[1,0,0]
	s_nop 0
	v_mul_f32_e32 v142, 0x4b800000, v159
	v_cmp_gt_f32_e64 s[4:5], s97, v159
	v_mul_f32_e32 v146, 0x45800000, v144
	v_cndmask_b32_e32 v144, v144, v146, vcc
	v_cndmask_b32_e64 v142, v159, v142, s[4:5]
	v_rsq_f32_e32 v142, v142
	v_cndmask_b32_e64 v152, v144, 1.0, s[34:35]
	v_cmp_gt_f32_e32 vcc, s97, v158
	ds_bpermute_b32 v159, v160, v140
	v_mul_f32_e32 v144, 0x45800000, v142
	v_cndmask_b32_e64 v142, v142, v144, s[4:5]
	v_cndmask_b32_e64 v150, v142, 1.0, s[34:35]
	v_mul_f32_e32 v142, 0x4b800000, v158
	v_cndmask_b32_e32 v142, v158, v142, vcc
	v_rsq_f32_e32 v142, v142
	ds_bpermute_b32 v158, v160, v140 offset:64
	v_pk_mul_f32 v[110:111], v[110:111], v[152:153] op_sel_hi:[1,0]
	v_pk_mul_f32 v[102:103], v[102:103], v[152:153] op_sel_hi:[1,0]
	v_mul_f32_e32 v144, 0x45800000, v142
	v_cndmask_b32_e32 v142, v142, v144, vcc
	s_waitcnt lgkmcnt(0)
; __device__ __forceinline__ float silu_f(float x) { return x * __builtin_amdgcn_rcpf(1.f + __builtin_amdgcn_exp2f(-LOG2E * x)); }
; __device__ __forceinline__ u32x4 pk8(const f32x4 a, const f32x4 b) { u32x4 w; w.x = pk2(a[0], a[1]); w.y = pk2(a[2], a[3]); w.z = pk2(b[0], b[1]); w.w = pk2(b[2], b[3]); return w; }
; __device__ __forceinline__ float pre_get(const Pre& p, int ai, int m, int fr) { return __shfl(p.v[ai], m * 16 + fr); }
; __device__ __forceinline__ float rstd_pre(const float* ss, float v) { return ss ? rsqrtf(v * (1.0f / 2048.0f) + 1e-6f) : 1.0f; }
;     __device__ __forceinline__ void operator()(const Acc& acc, const Unit& u, int wr, int wc, int fr, int fq, const Pre& pre) const {
;     ...
;         for (int ai = 0; ai < 2; ++ai)
; #pragma unroll
;             for (int m = 0; m < 4; ++m) rsq[ai][m] = rstd_pre(ss, pre_get(pre, ai, m, fr));
; #pragma unroll
;         for (int ai = 0; ai < 2; ++ai)
; #pragma unroll
;             for (int m = 0; m < 4; ++m) {
;                 f32x4 v0, v1; const float rs = rsq[ai][m];
; #pragma unroll
;                 for (int e = 0; e < 4; ++e) { v0[e] = silu_f(acc[ai][0][m][0][e] * rs) * (acc[ai][1][m][0][e] * rs); v1[e] = silu_f(acc[ai][0][m][1][e] * rs) * (acc[ai][1][m][1][e] * rs); }
;                 *(u32x4*)(O + (size_t)(row0 + ai * 128 + m * 16) * ldc + col0) = pk8(v0, v1);
	v_pk_fma_f32 v[158:159], v[158:159], s[8:9], v[156:157] op_sel_hi:[1,0,0]
	v_cndmask_b32_e64 v148, v142, 1.0, s[34:35]
	v_mul_f32_e32 v142, 0x4b800000, v159
	v_cmp_gt_f32_e64 s[4:5], s97, v159
	v_cmp_gt_f32_e32 vcc, s97, v158
	v_pk_mul_f32 v[106:107], v[106:107], v[152:153] op_sel_hi:[1,0]
	v_cndmask_b32_e64 v142, v159, v142, s[4:5]
	v_rsq_f32_e32 v142, v142
	ds_bpermute_b32 v159, v160, v140 offset:128
	v_pk_mul_f32 v[98:99], v[98:99], v[152:153] op_sel_hi:[1,0]
	v_pk_mul_f32 v[104:105], v[104:105], v[152:153] op_sel_hi:[1,0]
	v_mul_f32_e32 v144, 0x45800000, v142
	v_cndmask_b32_e64 v142, v142, v144, s[4:5]
	v_cndmask_b32_e64 v146, v142, 1.0, s[34:35]
	v_mul_f32_e32 v142, 0x4b800000, v158
	v_cndmask_b32_e32 v142, v158, v142, vcc
	ds_bpermute_b32 v158, v160, v140 offset:192
	v_rsq_f32_e32 v142, v142
	v_pk_mul_f32 v[100:101], v[100:101], v[152:153] op_sel_hi:[1,0]
	v_pk_mul_f32 v[94:95], v[94:95], v[150:151] op_sel_hi:[1,0]
	v_pk_mul_f32 v[86:87], v[86:87], v[150:151] op_sel_hi:[1,0]
	s_waitcnt lgkmcnt(0)
	v_pk_fma_f32 v[156:157], v[158:159], s[8:9], v[156:157] op_sel_hi:[1,0,0]
	v_mul_f32_e32 v144, 0x45800000, v142
	v_mul_f32_e32 v140, 0x4b800000, v157
	v_cmp_gt_f32_e64 s[4:5], s97, v157
	v_cndmask_b32_e32 v142, v142, v144, vcc
	v_cndmask_b32_e64 v144, v142, 1.0, s[34:35]
	v_cndmask_b32_e64 v140, v157, v140, s[4:5]
	v_rsq_f32_e32 v140, v140
	v_cmp_gt_f32_e32 vcc, s97, v156
	v_pk_mul_f32 v[90:91], v[90:91], v[150:151] op_sel_hi:[1,0]
	v_pk_mul_f32 v[82:83], v[82:83], v[150:151] op_sel_hi:[1,0]
	v_mul_f32_e32 v142, 0x45800000, v140
	v_cndmask_b32_e64 v140, v140, v142, s[4:5]
	v_cndmask_b32_e64 v142, v140, 1.0, s[34:35]
	v_mul_f32_e32 v140, 0x4b800000, v156
	v_cndmask_b32_e32 v140, v156, v140, vcc
	v_rsq_f32_e32 v140, v140
	v_lshl_or_b32 v156, s55, 7, v149
	v_ashrrev_i32_e32 v157, 31, v156
	v_pk_mul_f32 v[88:89], v[88:89], v[150:151] op_sel_hi:[1,0]
	v_mul_f32_e32 v155, 0x45800000, v140
	v_pk_mul_f32 v[126:127], v[126:127], v[154:155] op_sel_hi:[1,0]
	v_cndmask_b32_e32 v140, v140, v155, vcc
	v_mul_f32_e32 v155, 0xbfb8aa3b, v126
	v_exp_f32_e32 v155, v155
	v_pk_mul_f32 v[84:85], v[84:85], v[150:151] op_sel_hi:[1,0]
	v_pk_mul_f32 v[78:79], v[78:79], v[148:149] op_sel_hi:[1,0]
	v_pk_mul_f32 v[70:71], v[70:71], v[148:149] op_sel_hi:[1,0]
	v_add_f32_e32 v155, 1.0, v155
	v_rcp_f32_e32 v158, v155
	v_mul_f32_e32 v155, 0xbfb8aa3b, v127
	v_exp_f32_e32 v155, v155
	v_pk_mul_f32 v[74:75], v[74:75], v[148:149] op_sel_hi:[1,0]
	v_pk_mul_f32 v[66:67], v[66:67], v[148:149] op_sel_hi:[1,0]
	v_pk_mul_f32 v[72:73], v[72:73], v[148:149] op_sel_hi:[1,0]
	v_add_f32_e32 v155, 1.0, v155
	v_rcp_f32_e32 v159, v155
	v_pk_mul_f32 v[118:119], v[118:119], v[154:155] op_sel_hi:[1,0]
	v_pk_mul_f32 v[122:123], v[122:123], v[154:155] op_sel_hi:[1,0]
	v_pk_mul_f32 v[114:115], v[114:115], v[154:155] op_sel_hi:[1,0]
	v_pk_mul_f32 v[126:127], v[126:127], v[158:159]
	v_pk_mul_f32 v[120:121], v[120:121], v[154:155] op_sel_hi:[1,0]
	v_pk_mul_f32 v[118:119], v[118:119], v[126:127]
	v_mul_f32_e32 v126, 0xbfb8aa3b, v122
	v_mul_f32_e32 v127, 0xbfb8aa3b, v123
	v_exp_f32_e32 v126, v126
	v_exp_f32_e32 v127, v127
	v_pk_mul_f32 v[116:117], v[116:117], v[154:155] op_sel_hi:[1,0]
	v_cvt_pk_bf16_f32 v118, v118, v119
	v_add_f32_e32 v126, 1.0, v126
	v_add_f32_e32 v127, 1.0, v127
	v_rcp_f32_e32 v126, v126
	v_rcp_f32_e32 v127, v127
	v_pk_mul_f32 v[68:69], v[68:69], v[148:149] op_sel_hi:[1,0]
	v_pk_mul_f32 v[62:63], v[62:63], v[146:147] op_sel_hi:[1,0]
	v_pk_mul_f32 v[54:55], v[54:55], v[146:147] op_sel_hi:[1,0]
	v_pk_mul_f32 v[122:123], v[122:123], v[126:127]
	v_pk_mul_f32 v[58:59], v[58:59], v[146:147] op_sel_hi:[1,0]
	v_pk_mul_f32 v[114:115], v[114:115], v[122:123]
	v_pk_mul_f32 v[122:123], v[128:129], v[154:155] op_sel_hi:[1,0]
	v_pk_mul_f32 v[50:51], v[50:51], v[146:147] op_sel_hi:[1,0]
	v_mul_f32_e32 v126, 0xbfb8aa3b, v122
	v_mul_f32_e32 v127, 0xbfb8aa3b, v123
	v_exp_f32_e32 v126, v126
	v_exp_f32_e32 v127, v127
	v_pk_mul_f32 v[56:57], v[56:57], v[146:147] op_sel_hi:[1,0]
	v_pk_mul_f32 v[52:53], v[52:53], v[146:147] op_sel_hi:[1,0]
	v_add_f32_e32 v126, 1.0, v126
	v_add_f32_e32 v127, 1.0, v127
	v_rcp_f32_e32 v126, v126
	v_rcp_f32_e32 v127, v127
	v_pk_mul_f32 v[46:47], v[46:47], v[144:145] op_sel_hi:[1,0]
	v_pk_mul_f32 v[38:39], v[38:39], v[144:145] op_sel_hi:[1,0]
	v_pk_mul_f32 v[42:43], v[42:43], v[144:145] op_sel_hi:[1,0]
	v_pk_mul_f32 v[122:123], v[122:123], v[126:127]
	v_pk_mul_f32 v[34:35], v[34:35], v[144:145] op_sel_hi:[1,0]
	v_pk_mul_f32 v[120:121], v[120:121], v[122:123]
	v_pk_mul_f32 v[122:123], v[124:125], v[154:155] op_sel_hi:[1,0]
	v_cvt_pk_bf16_f32 v119, v120, v121
	v_mul_f32_e32 v124, 0xbfb8aa3b, v122
	v_mul_f32_e32 v125, 0xbfb8aa3b, v123
	v_exp_f32_e32 v124, v124
	v_exp_f32_e32 v125, v125
	v_cvt_pk_bf16_f32 v120, v114, v115
	v_ashrrev_i32_e32 v114, 31, v153
	v_add_f32_e32 v124, 1.0, v124
	v_add_f32_e32 v125, 1.0, v125
	v_rcp_f32_e32 v124, v124
	v_rcp_f32_e32 v125, v125
	v_pk_mul_f32 v[40:41], v[40:41], v[144:145] op_sel_hi:[1,0]
	v_pk_mul_f32 v[36:37], v[36:37], v[144:145] op_sel_hi:[1,0]
	v_pk_mul_f32 v[30:31], v[30:31], v[142:143] op_sel_hi:[1,0]
	v_pk_mul_f32 v[122:123], v[122:123], v[124:125]
	v_pk_mul_f32 v[22:23], v[22:23], v[142:143] op_sel_hi:[1,0]
	v_pk_mul_f32 v[116:117], v[116:117], v[122:123]
	v_pk_mul_f32 v[26:27], v[26:27], v[142:143] op_sel_hi:[1,0]
	v_cvt_pk_bf16_f32 v121, v116, v117
	v_mul_lo_u32 v116, s12, v114
	v_mul_lo_u32 v117, s13, v153
	v_mad_u64_u32 v[114:115], s[4:5], s12, v153, 0
	v_add3_u32 v115, v115, v116, v117
	v_mul_f32_e32 v117, 0xbfb8aa3b, v110
	v_exp_f32_e32 v117, v117
	v_lshl_add_u64 v[122:123], v[114:115], 1, s[62:63]
	v_lshlrev_b64 v[114:115], 1, v[156:157]
; __device__ __forceinline__ float silu_f(float x) { return x * __builtin_amdgcn_rcpf(1.f + __builtin_amdgcn_exp2f(-LOG2E * x)); }
; __device__ __forceinline__ u32x4 pk8(const f32x4 a, const f32x4 b) { u32x4 w; w.x = pk2(a[0], a[1]); w.y = pk2(a[2], a[3]); w.z = pk2(b[0], b[1]); w.w = pk2(b[2], b[3]); return w; }
;     __device__ __forceinline__ void operator()(const Acc& acc, const Unit& u, int wr, int wc, int fr, int fq, const Pre& pre) const {
;     ...
; #pragma unroll
;         for (int ai = 0; ai < 2; ++ai)
; #pragma unroll
;             for (int m = 0; m < 4; ++m) {
;                 f32x4 v0, v1; const float rs = rsq[ai][m];
; #pragma unroll
;                 for (int e = 0; e < 4; ++e) { v0[e] = silu_f(acc[ai][0][m][0][e] * rs) * (acc[ai][1][m][0][e] * rs); v1[e] = silu_f(acc[ai][0][m][1][e] * rs) * (acc[ai][1][m][1][e] * rs); }
;                 *(u32x4*)(O + (size_t)(row0 + ai * 128 + m * 16) * ldc + col0) = pk8(v0, v1);
;             }
	v_lshl_add_u64 v[122:123], v[122:123], 0, v[114:115]
	v_add_f32_e32 v117, 1.0, v117
	global_store_dwordx4 v[122:123], v[118:121], off
	v_pk_mul_f32 v[18:19], v[18:19], v[142:143] op_sel_hi:[1,0]
	v_pk_mul_f32 v[24:25], v[24:25], v[142:143] op_sel_hi:[1,0]
	v_rcp_f32_e32 v118, v117
	v_mul_f32_e32 v117, 0xbfb8aa3b, v111
	v_exp_f32_e32 v117, v117
	v_pk_mul_f32 v[20:21], v[20:21], v[142:143] op_sel_hi:[1,0]
	v_cndmask_b32_e64 v140, v140, 1.0, s[34:35]
	v_pk_mul_f32 v[14:15], v[14:15], v[140:141] op_sel_hi:[1,0]
	v_add_f32_e32 v117, 1.0, v117
	v_rcp_f32_e32 v119, v117
	v_pk_mul_f32 v[6:7], v[6:7], v[140:141] op_sel_hi:[1,0]
	v_pk_mul_f32 v[10:11], v[10:11], v[140:141] op_sel_hi:[1,0]
	v_pk_mul_f32 v[2:3], v[2:3], v[140:141] op_sel_hi:[1,0]
	v_pk_mul_f32 v[110:111], v[110:111], v[118:119]
	v_pk_mul_f32 v[8:9], v[8:9], v[140:141] op_sel_hi:[1,0]
	v_pk_mul_f32 v[102:103], v[102:103], v[110:111]
	v_mul_f32_e32 v110, 0xbfb8aa3b, v106
	v_mul_f32_e32 v111, 0xbfb8aa3b, v107
	v_exp_f32_e32 v110, v110
	v_exp_f32_e32 v111, v111
	v_pk_mul_f32 v[4:5], v[4:5], v[140:141] op_sel_hi:[1,0]
	s_and_b64 vcc, exec, s[0:1]
	v_add_f32_e32 v110, 1.0, v110
	v_add_f32_e32 v111, 1.0, v111
	v_rcp_f32_e32 v110, v110
	v_rcp_f32_e32 v111, v111
	s_mov_b32 s55, s79
	v_pk_mul_f32 v[106:107], v[106:107], v[110:111]
	s_nop 0
	v_pk_mul_f32 v[106:107], v[98:99], v[106:107]
	v_pk_mul_f32 v[98:99], v[112:113], v[152:153] op_sel_hi:[1,0]
	s_nop 0
	v_mul_f32_e32 v110, 0xbfb8aa3b, v98
	v_mul_f32_e32 v111, 0xbfb8aa3b, v99
	v_exp_f32_e32 v110, v110
	v_exp_f32_e32 v111, v111
	v_add_f32_e32 v110, 1.0, v110
	v_add_f32_e32 v111, 1.0, v111
	v_rcp_f32_e32 v110, v110
	v_rcp_f32_e32 v111, v111
	s_nop 0
	v_pk_mul_f32 v[98:99], v[98:99], v[110:111]
	s_nop 0
	v_pk_mul_f32 v[104:105], v[104:105], v[98:99]
	v_pk_mul_f32 v[98:99], v[108:109], v[152:153] op_sel_hi:[1,0]
	s_nop 0
	v_mul_f32_e32 v108, 0xbfb8aa3b, v98
	v_mul_f32_e32 v109, 0xbfb8aa3b, v99
	v_exp_f32_e32 v108, v108
	v_exp_f32_e32 v109, v109
	v_add_f32_e32 v108, 1.0, v108
	v_add_f32_e32 v109, 1.0, v109
	v_rcp_f32_e32 v108, v108
	v_rcp_f32_e32 v109, v109
	s_nop 0
	v_pk_mul_f32 v[98:99], v[98:99], v[108:109]
	s_nop 0
	v_pk_mul_f32 v[108:109], v[100:101], v[98:99]
	v_cvt_pk_bf16_f32 v98, v102, v103
	v_or_b32_e32 v102, 16, v153
	v_cvt_pk_bf16_f32 v99, v104, v105
	v_mul_lo_u32 v104, s13, v102
	v_mad_u64_u32 v[102:103], s[4:5], s12, v102, 0
	v_add3_u32 v103, v103, v116, v104
	v_lshl_add_u64 v[102:103], v[102:103], 1, s[62:63]
	v_cvt_pk_bf16_f32 v100, v106, v107
	v_cvt_pk_bf16_f32 v101, v108, v109
	v_lshl_add_u64 v[102:103], v[102:103], 0, v[114:115]
	global_store_dwordx4 v[102:103], v[98:101], off
	s_nop 1
	v_mul_f32_e32 v98, 0xbfb8aa3b, v94
	v_mul_f32_e32 v99, 0xbfb8aa3b, v95
	v_exp_f32_e32 v98, v98
	v_exp_f32_e32 v99, v99
	v_add_f32_e32 v98, 1.0, v98
	v_add_f32_e32 v99, 1.0, v99
	v_rcp_f32_e32 v98, v98
	v_rcp_f32_e32 v99, v99
	s_nop 0
	v_pk_mul_f32 v[94:95], v[94:95], v[98:99]
	s_nop 0
	v_pk_mul_f32 v[86:87], v[86:87], v[94:95]
	v_mul_f32_e32 v94, 0xbfb8aa3b, v90
	v_mul_f32_e32 v95, 0xbfb8aa3b, v91
	v_exp_f32_e32 v94, v94
	v_exp_f32_e32 v95, v95
	v_add_f32_e32 v94, 1.0, v94
	v_add_f32_e32 v95, 1.0, v95
	v_rcp_f32_e32 v94, v94
	v_rcp_f32_e32 v95, v95
	s_nop 0
	v_pk_mul_f32 v[90:91], v[90:91], v[94:95]
	s_nop 0
	v_pk_mul_f32 v[90:91], v[82:83], v[90:91]
	v_pk_mul_f32 v[82:83], v[96:97], v[150:151] op_sel_hi:[1,0]
	s_nop 0
	v_mul_f32_e32 v94, 0xbfb8aa3b, v82
	v_mul_f32_e32 v95, 0xbfb8aa3b, v83
	v_exp_f32_e32 v94, v94
	v_exp_f32_e32 v95, v95
	v_add_f32_e32 v94, 1.0, v94
	v_add_f32_e32 v95, 1.0, v95
	v_rcp_f32_e32 v94, v94
	v_rcp_f32_e32 v95, v95
	s_nop 0
	v_pk_mul_f32 v[82:83], v[82:83], v[94:95]
	s_nop 0
	v_pk_mul_f32 v[88:89], v[88:89], v[82:83]
	v_pk_mul_f32 v[82:83], v[92:93], v[150:151] op_sel_hi:[1,0]
	s_nop 0
	v_mul_f32_e32 v92, 0xbfb8aa3b, v82
	v_mul_f32_e32 v93, 0xbfb8aa3b, v83
	v_exp_f32_e32 v92, v92
	v_exp_f32_e32 v93, v93
	v_add_f32_e32 v92, 1.0, v92
	v_add_f32_e32 v93, 1.0, v93
	v_rcp_f32_e32 v92, v92
	v_rcp_f32_e32 v93, v93
	s_nop 0
	v_pk_mul_f32 v[82:83], v[82:83], v[92:93]
	s_nop 0
	v_pk_mul_f32 v[92:93], v[84:85], v[82:83]
	v_cvt_pk_bf16_f32 v82, v86, v87
	v_or_b32_e32 v86, 32, v153
	v_cvt_pk_bf16_f32 v83, v88, v89
	v_mul_lo_u32 v88, s13, v86
	v_mad_u64_u32 v[86:87], s[4:5], s12, v86, 0
	v_add3_u32 v87, v87, v116, v88
	v_lshl_add_u64 v[86:87], v[86:87], 1, s[62:63]
	v_cvt_pk_bf16_f32 v84, v90, v91
	v_cvt_pk_bf16_f32 v85, v92, v93
	v_lshl_add_u64 v[86:87], v[86:87], 0, v[114:115]
	global_store_dwordx4 v[86:87], v[82:85], off
	s_nop 1
	v_mul_f32_e32 v82, 0xbfb8aa3b, v78
	v_mul_f32_e32 v83, 0xbfb8aa3b, v79
	v_exp_f32_e32 v82, v82
	v_exp_f32_e32 v83, v83
	v_add_f32_e32 v82, 1.0, v82
	v_add_f32_e32 v83, 1.0, v83
	v_rcp_f32_e32 v82, v82
	v_rcp_f32_e32 v83, v83
	s_nop 0
	v_pk_mul_f32 v[78:79], v[78:79], v[82:83]
	s_nop 0
	v_pk_mul_f32 v[70:71], v[70:71], v[78:79]
	v_mul_f32_e32 v78, 0xbfb8aa3b, v74
	v_mul_f32_e32 v79, 0xbfb8aa3b, v75
	v_exp_f32_e32 v78, v78
	v_exp_f32_e32 v79, v79
	v_add_f32_e32 v78, 1.0, v78
	v_add_f32_e32 v79, 1.0, v79
	v_rcp_f32_e32 v78, v78
	v_rcp_f32_e32 v79, v79
	s_nop 0
	v_pk_mul_f32 v[74:75], v[74:75], v[78:79]
	s_nop 0
	v_pk_mul_f32 v[74:75], v[66:67], v[74:75]
	v_pk_mul_f32 v[66:67], v[80:81], v[148:149] op_sel_hi:[1,0]
	s_nop 0
	v_mul_f32_e32 v78, 0xbfb8aa3b, v66
	v_mul_f32_e32 v79, 0xbfb8aa3b, v67
	v_exp_f32_e32 v78, v78
	v_exp_f32_e32 v79, v79
	v_add_f32_e32 v78, 1.0, v78
	v_add_f32_e32 v79, 1.0, v79
	v_rcp_f32_e32 v78, v78
	v_rcp_f32_e32 v79, v79
	s_nop 0
	v_pk_mul_f32 v[66:67], v[66:67], v[78:79]
	s_nop 0
	v_pk_mul_f32 v[72:73], v[72:73], v[66:67]
	v_pk_mul_f32 v[66:67], v[76:77], v[148:149] op_sel_hi:[1,0]
; __device__ __forceinline__ float silu_f(float x) { return x * __builtin_amdgcn_rcpf(1.f + __builtin_amdgcn_exp2f(-LOG2E * x)); }
; __device__ __forceinline__ u32x4 pk8(const f32x4 a, const f32x4 b) { u32x4 w; w.x = pk2(a[0], a[1]); w.y = pk2(a[2], a[3]); w.z = pk2(b[0], b[1]); w.w = pk2(b[2], b[3]); return w; }
;     __device__ __forceinline__ void operator()(const Acc& acc, const Unit& u, int wr, int wc, int fr, int fq, const Pre& pre) const {
;     ...
; #pragma unroll
;         for (int ai = 0; ai < 2; ++ai)
; #pragma unroll
;             for (int m = 0; m < 4; ++m) {
;                 f32x4 v0, v1; const float rs = rsq[ai][m];
; #pragma unroll
;                 for (int e = 0; e < 4; ++e) { v0[e] = silu_f(acc[ai][0][m][0][e] * rs) * (acc[ai][1][m][0][e] * rs); v1[e] = silu_f(acc[ai][0][m][1][e] * rs) * (acc[ai][1][m][1][e] * rs); }
;                 *(u32x4*)(O + (size_t)(row0 + ai * 128 + m * 16) * ldc + col0) = pk8(v0, v1);
;             }
	s_nop 0
	v_mul_f32_e32 v76, 0xbfb8aa3b, v66
	v_mul_f32_e32 v77, 0xbfb8aa3b, v67
	v_exp_f32_e32 v76, v76
	v_exp_f32_e32 v77, v77
	v_add_f32_e32 v76, 1.0, v76
	v_add_f32_e32 v77, 1.0, v77
	v_rcp_f32_e32 v76, v76
	v_rcp_f32_e32 v77, v77
	s_nop 0
	v_pk_mul_f32 v[66:67], v[66:67], v[76:77]
	s_nop 0
	v_pk_mul_f32 v[76:77], v[68:69], v[66:67]
	v_cvt_pk_bf16_f32 v66, v70, v71
	v_or_b32_e32 v70, 48, v153
	v_cvt_pk_bf16_f32 v67, v72, v73
	v_mul_lo_u32 v72, s13, v70
	v_mad_u64_u32 v[70:71], s[4:5], s12, v70, 0
	v_add3_u32 v71, v71, v116, v72
	v_lshl_add_u64 v[70:71], v[70:71], 1, s[62:63]
	v_cvt_pk_bf16_f32 v68, v74, v75
	v_cvt_pk_bf16_f32 v69, v76, v77
	v_lshl_add_u64 v[70:71], v[70:71], 0, v[114:115]
	global_store_dwordx4 v[70:71], v[66:69], off
	s_nop 1
	v_mul_f32_e32 v66, 0xbfb8aa3b, v62
	v_mul_f32_e32 v67, 0xbfb8aa3b, v63
	v_exp_f32_e32 v66, v66
	v_exp_f32_e32 v67, v67
	v_add_u32_e32 v68, 0x80, v153
	v_add_f32_e32 v66, 1.0, v66
	v_add_f32_e32 v67, 1.0, v67
	v_rcp_f32_e32 v66, v66
	v_rcp_f32_e32 v67, v67
	s_nop 0
	v_pk_mul_f32 v[62:63], v[62:63], v[66:67]
	s_nop 0
	v_pk_mul_f32 v[54:55], v[54:55], v[62:63]
	v_mul_f32_e32 v62, 0xbfb8aa3b, v58
	v_mul_f32_e32 v63, 0xbfb8aa3b, v59
	v_exp_f32_e32 v62, v62
	v_exp_f32_e32 v63, v63
	v_add_f32_e32 v62, 1.0, v62
	v_add_f32_e32 v63, 1.0, v63
	v_rcp_f32_e32 v62, v62
	v_rcp_f32_e32 v63, v63
	s_nop 0
	v_pk_mul_f32 v[58:59], v[58:59], v[62:63]
	s_nop 0
	v_pk_mul_f32 v[58:59], v[50:51], v[58:59]
	v_pk_mul_f32 v[50:51], v[64:65], v[146:147] op_sel_hi:[1,0]
	s_nop 0
	v_mul_f32_e32 v62, 0xbfb8aa3b, v50
	v_mul_f32_e32 v63, 0xbfb8aa3b, v51
	v_exp_f32_e32 v62, v62
	v_exp_f32_e32 v63, v63
	v_add_f32_e32 v62, 1.0, v62
	v_add_f32_e32 v63, 1.0, v63
	v_rcp_f32_e32 v62, v62
	v_rcp_f32_e32 v63, v63
	s_nop 0
	v_pk_mul_f32 v[50:51], v[50:51], v[62:63]
	s_nop 0
	v_pk_mul_f32 v[56:57], v[56:57], v[50:51]
	v_pk_mul_f32 v[50:51], v[60:61], v[146:147] op_sel_hi:[1,0]
	s_nop 0
	v_mul_f32_e32 v60, 0xbfb8aa3b, v50
	v_mul_f32_e32 v61, 0xbfb8aa3b, v51
	v_exp_f32_e32 v60, v60
	v_exp_f32_e32 v61, v61
	v_add_f32_e32 v60, 1.0, v60
	v_add_f32_e32 v61, 1.0, v61
	v_rcp_f32_e32 v60, v60
	v_rcp_f32_e32 v61, v61
	s_nop 0
	v_pk_mul_f32 v[50:51], v[50:51], v[60:61]
	s_nop 0
	v_pk_mul_f32 v[60:61], v[52:53], v[50:51]
	v_cvt_pk_bf16_f32 v50, v54, v55
	v_ashrrev_i32_e32 v54, 31, v68
	v_cvt_pk_bf16_f32 v51, v56, v57
	v_mul_lo_u32 v56, s12, v54
	v_mul_lo_u32 v57, s13, v68
	v_mad_u64_u32 v[54:55], s[4:5], s12, v68, 0
	v_add3_u32 v55, v55, v56, v57
	v_lshl_add_u64 v[54:55], v[54:55], 1, s[62:63]
	v_cvt_pk_bf16_f32 v52, v58, v59
	v_cvt_pk_bf16_f32 v53, v60, v61
	v_lshl_add_u64 v[54:55], v[54:55], 0, v[114:115]
	global_store_dwordx4 v[54:55], v[50:53], off
	s_nop 1
	v_mul_f32_e32 v50, 0xbfb8aa3b, v46
	v_mul_f32_e32 v51, 0xbfb8aa3b, v47
	v_exp_f32_e32 v50, v50
	v_exp_f32_e32 v51, v51
	v_add_f32_e32 v50, 1.0, v50
	v_add_f32_e32 v51, 1.0, v51
	v_rcp_f32_e32 v50, v50
	v_rcp_f32_e32 v51, v51
	s_nop 0
	v_pk_mul_f32 v[46:47], v[46:47], v[50:51]
	s_nop 0
	v_pk_mul_f32 v[38:39], v[38:39], v[46:47]
	v_mul_f32_e32 v46, 0xbfb8aa3b, v42
	v_mul_f32_e32 v47, 0xbfb8aa3b, v43
	v_exp_f32_e32 v46, v46
	v_exp_f32_e32 v47, v47
	v_add_f32_e32 v46, 1.0, v46
	v_add_f32_e32 v47, 1.0, v47
	v_rcp_f32_e32 v46, v46
	v_rcp_f32_e32 v47, v47
	s_nop 0
	v_pk_mul_f32 v[42:43], v[42:43], v[46:47]
	s_nop 0
	v_pk_mul_f32 v[42:43], v[34:35], v[42:43]
	v_pk_mul_f32 v[34:35], v[48:49], v[144:145] op_sel_hi:[1,0]
	s_nop 0
	v_mul_f32_e32 v46, 0xbfb8aa3b, v34
	v_mul_f32_e32 v47, 0xbfb8aa3b, v35
	v_exp_f32_e32 v46, v46
	v_exp_f32_e32 v47, v47
	v_add_f32_e32 v46, 1.0, v46
	v_add_f32_e32 v47, 1.0, v47
	v_rcp_f32_e32 v46, v46
	v_rcp_f32_e32 v47, v47
	s_nop 0
	v_pk_mul_f32 v[34:35], v[34:35], v[46:47]
	s_nop 0
	v_pk_mul_f32 v[40:41], v[40:41], v[34:35]
	v_pk_mul_f32 v[34:35], v[44:45], v[144:145] op_sel_hi:[1,0]
	s_nop 0
	v_mul_f32_e32 v44, 0xbfb8aa3b, v34
	v_mul_f32_e32 v45, 0xbfb8aa3b, v35
	v_exp_f32_e32 v44, v44
	v_exp_f32_e32 v45, v45
	v_add_f32_e32 v44, 1.0, v44
	v_add_f32_e32 v45, 1.0, v45
	v_rcp_f32_e32 v44, v44
	v_rcp_f32_e32 v45, v45
	s_nop 0
	v_pk_mul_f32 v[34:35], v[34:35], v[44:45]
	s_nop 0
	v_pk_mul_f32 v[44:45], v[36:37], v[34:35]
	v_cvt_pk_bf16_f32 v34, v38, v39
	v_add_u32_e32 v38, 0x90, v153
	v_ashrrev_i32_e32 v39, 31, v38
; __device__ __forceinline__ float silu_f(float x) { return x * __builtin_amdgcn_rcpf(1.f + __builtin_amdgcn_exp2f(-LOG2E * x)); }
; __device__ __forceinline__ u32x4 pk8(const f32x4 a, const f32x4 b) { u32x4 w; w.x = pk2(a[0], a[1]); w.y = pk2(a[2], a[3]); w.z = pk2(b[0], b[1]); w.w = pk2(b[2], b[3]); return w; }
;     __device__ __forceinline__ void operator()(const Acc& acc, const Unit& u, int wr, int wc, int fr, int fq, const Pre& pre) const {
;     ...
; #pragma unroll
;         for (int ai = 0; ai < 2; ++ai)
; #pragma unroll
;             for (int m = 0; m < 4; ++m) {
;                 f32x4 v0, v1; const float rs = rsq[ai][m];
; #pragma unroll
;                 for (int e = 0; e < 4; ++e) { v0[e] = silu_f(acc[ai][0][m][0][e] * rs) * (acc[ai][1][m][0][e] * rs); v1[e] = silu_f(acc[ai][0][m][1][e] * rs) * (acc[ai][1][m][1][e] * rs); }
;                 *(u32x4*)(O + (size_t)(row0 + ai * 128 + m * 16) * ldc + col0) = pk8(v0, v1);
;             }
	v_cvt_pk_bf16_f32 v35, v40, v41
	v_mul_lo_u32 v40, s12, v39
	v_mul_lo_u32 v41, s13, v38
	v_mad_u64_u32 v[38:39], s[4:5], s12, v38, 0
	v_add3_u32 v39, v39, v40, v41
	v_lshl_add_u64 v[38:39], v[38:39], 1, s[62:63]
	v_cvt_pk_bf16_f32 v36, v42, v43
	v_cvt_pk_bf16_f32 v37, v44, v45
	v_lshl_add_u64 v[38:39], v[38:39], 0, v[114:115]
	global_store_dwordx4 v[38:39], v[34:37], off
	s_nop 1
	v_mul_f32_e32 v34, 0xbfb8aa3b, v30
	v_mul_f32_e32 v35, 0xbfb8aa3b, v31
	v_exp_f32_e32 v34, v34
	v_exp_f32_e32 v35, v35
	v_add_f32_e32 v34, 1.0, v34
	v_add_f32_e32 v35, 1.0, v35
	v_rcp_f32_e32 v34, v34
	v_rcp_f32_e32 v35, v35
	s_nop 0
	v_pk_mul_f32 v[30:31], v[30:31], v[34:35]
	s_nop 0
	v_pk_mul_f32 v[22:23], v[22:23], v[30:31]
	v_mul_f32_e32 v30, 0xbfb8aa3b, v26
	v_mul_f32_e32 v31, 0xbfb8aa3b, v27
	v_exp_f32_e32 v30, v30
	v_exp_f32_e32 v31, v31
	v_add_f32_e32 v30, 1.0, v30
	v_add_f32_e32 v31, 1.0, v31
	v_rcp_f32_e32 v30, v30
	v_rcp_f32_e32 v31, v31
	s_nop 0
	v_pk_mul_f32 v[26:27], v[26:27], v[30:31]
	s_nop 0
	v_pk_mul_f32 v[26:27], v[18:19], v[26:27]
	v_pk_mul_f32 v[18:19], v[32:33], v[142:143] op_sel_hi:[1,0]
	s_nop 0
	v_mul_f32_e32 v30, 0xbfb8aa3b, v18
	v_mul_f32_e32 v31, 0xbfb8aa3b, v19
	v_exp_f32_e32 v30, v30
	v_exp_f32_e32 v31, v31
	v_add_f32_e32 v30, 1.0, v30
	v_add_f32_e32 v31, 1.0, v31
	v_rcp_f32_e32 v30, v30
	v_rcp_f32_e32 v31, v31
	s_nop 0
	v_pk_mul_f32 v[18:19], v[18:19], v[30:31]
	s_nop 0
	v_pk_mul_f32 v[24:25], v[24:25], v[18:19]
	v_pk_mul_f32 v[18:19], v[28:29], v[142:143] op_sel_hi:[1,0]
	s_nop 0
	v_mul_f32_e32 v28, 0xbfb8aa3b, v18
	v_mul_f32_e32 v29, 0xbfb8aa3b, v19
	v_exp_f32_e32 v28, v28
	v_exp_f32_e32 v29, v29
	v_add_f32_e32 v28, 1.0, v28
	v_add_f32_e32 v29, 1.0, v29
	v_rcp_f32_e32 v28, v28
	v_rcp_f32_e32 v29, v29
	s_nop 0
	v_pk_mul_f32 v[18:19], v[18:19], v[28:29]
	s_nop 0
	v_pk_mul_f32 v[28:29], v[20:21], v[18:19]
	v_cvt_pk_bf16_f32 v18, v22, v23
	v_add_u32_e32 v22, 0xa0, v153
	v_ashrrev_i32_e32 v23, 31, v22
	v_cvt_pk_bf16_f32 v19, v24, v25
	v_mul_lo_u32 v24, s12, v23
	v_mul_lo_u32 v25, s13, v22
	v_mad_u64_u32 v[22:23], s[4:5], s12, v22, 0
	v_add3_u32 v23, v23, v24, v25
	v_lshl_add_u64 v[22:23], v[22:23], 1, s[62:63]
	v_cvt_pk_bf16_f32 v20, v26, v27
	v_cvt_pk_bf16_f32 v21, v28, v29
	v_lshl_add_u64 v[22:23], v[22:23], 0, v[114:115]
	global_store_dwordx4 v[22:23], v[18:21], off
	s_nop 1
	v_mul_f32_e32 v18, 0xbfb8aa3b, v14
	v_mul_f32_e32 v19, 0xbfb8aa3b, v15
	v_exp_f32_e32 v18, v18
	v_exp_f32_e32 v19, v19
	v_add_f32_e32 v18, 1.0, v18
	v_add_f32_e32 v19, 1.0, v19
	v_rcp_f32_e32 v18, v18
	v_rcp_f32_e32 v19, v19
	s_nop 0
	v_pk_mul_f32 v[14:15], v[14:15], v[18:19]
	s_nop 0
	v_pk_mul_f32 v[6:7], v[6:7], v[14:15]
	v_mul_f32_e32 v14, 0xbfb8aa3b, v10
	v_mul_f32_e32 v15, 0xbfb8aa3b, v11
	v_exp_f32_e32 v14, v14
	v_exp_f32_e32 v15, v15
	v_add_f32_e32 v14, 1.0, v14
	v_add_f32_e32 v15, 1.0, v15
	v_rcp_f32_e32 v14, v14
	v_rcp_f32_e32 v15, v15
	s_nop 0
	v_pk_mul_f32 v[10:11], v[10:11], v[14:15]
	s_nop 0
	v_pk_mul_f32 v[10:11], v[2:3], v[10:11]
	v_pk_mul_f32 v[2:3], v[16:17], v[140:141] op_sel_hi:[1,0]
	s_nop 0
	v_mul_f32_e32 v14, 0xbfb8aa3b, v2
	v_mul_f32_e32 v15, 0xbfb8aa3b, v3
	v_exp_f32_e32 v14, v14
	v_exp_f32_e32 v15, v15
	v_add_f32_e32 v14, 1.0, v14
	v_add_f32_e32 v15, 1.0, v15
	v_rcp_f32_e32 v14, v14
	v_rcp_f32_e32 v15, v15
	s_nop 0
	v_pk_mul_f32 v[2:3], v[2:3], v[14:15]
	s_nop 0
	v_pk_mul_f32 v[8:9], v[8:9], v[2:3]
	v_pk_mul_f32 v[2:3], v[12:13], v[140:141] op_sel_hi:[1,0]
	s_nop 0
	v_mul_f32_e32 v12, 0xbfb8aa3b, v2
	v_mul_f32_e32 v13, 0xbfb8aa3b, v3
	v_exp_f32_e32 v12, v12
	v_exp_f32_e32 v13, v13
	v_add_f32_e32 v12, 1.0, v12
	v_add_f32_e32 v13, 1.0, v13
	v_rcp_f32_e32 v12, v12
	v_rcp_f32_e32 v13, v13
	s_nop 0
	v_pk_mul_f32 v[2:3], v[2:3], v[12:13]
	s_nop 0
	v_pk_mul_f32 v[12:13], v[4:5], v[2:3]
	v_cvt_pk_bf16_f32 v2, v6, v7
	v_add_u32_e32 v6, 0xb0, v153
	v_ashrrev_i32_e32 v7, 31, v6
	v_cvt_pk_bf16_f32 v3, v8, v9
	v_mul_lo_u32 v8, s12, v7
	v_mul_lo_u32 v9, s13, v6
	v_mad_u64_u32 v[6:7], s[4:5], s12, v6, 0
	v_add3_u32 v7, v7, v8, v9
	v_lshl_add_u64 v[6:7], v[6:7], 1, s[62:63]
	v_cvt_pk_bf16_f32 v4, v10, v11
	v_cvt_pk_bf16_f32 v5, v12, v13
	v_lshl_add_u64 v[6:7], v[6:7], 0, v[114:115]
	s_mov_b64 s[4:5], s[64:65]
	global_store_dwordx4 v[6:7], v[2:5], off
	s_cbranch_vccz .LBB0_813
	s_branch .LBB0_828
